# phase 2 unit prologue: token-shift loads and the three previous-token ushort loads waited for once; LoRA weight rows and decay bias loads issued before the workgroup barrier
# speedup vs baseline: 1.0054x; 1.0005x over previous
; DI float rcpf_(float x) { return __builtin_amdgcn_rcpf(x); }
; DI void ld_cur_prev8(const Params& p, int row, int col, int mode, int sb, float* cur, float* prev) {
;     const u16* proj = (const u16*)(p.ws + W_PROJ);
;     unpack8(*(const uint4*)(proj + (size_t)row * NC + col), cur);
;     if (mode == 0) unpack8(*(const uint4*)(proj + (size_t)(row - 1) * NC + col), prev);
;     else if (mode == 1) { for (int i = 0; i < 8; ++i) prev[i] = 0.f; }
;     else { const float* s = p.st_shift + (size_t)sb * 1664 + (col - C_R); const float4 a = *(const float4*)s, b = *(const float4*)(s + 4);
;         prev[0] = a.x; prev[1] = a.y; prev[2] = a.z; prev[3] = a.w; prev[4] = b.x; prev[5] = b.y; prev[6] = b.z; prev[7] = b.w; }
; }
; DI void phase_rwkv_prep(const Params& p, char* lds) {
;     ...
;                     ld_cur_prev8(p, row0 + t, C_WD + cw, mode, b, cur, prv);
;                     { const float4 ma = *(const float4*)(p.mix + 1536 + cw), mb = *(const float4*)(p.mix + 1540 + cw); const float mx_[8] = {ma.x, ma.y, ma.z, ma.w, mb.x, mb.y, mb.z, mb.w};
; #pragma unroll
;                     for (int i = 0; i < 8; ++i) { const float x = cur[i] + (prv[i] - cur[i]) * mx_[i]; const float e2 = __expf(2.f * x); xw[i] = 1.f - 2.f * rcpf_(e2 + 1.f); } }
;                     ld_cur_prev8(p, row0 + t, C_AD + cw, mode, b, cur, prv);
;                     { const float4 ma = *(const float4*)(p.mix + 1600 + cw), mb = *(const float4*)(p.mix + 1604 + cw); const float mx_[8] = {ma.x, ma.y, ma.z, ma.w, mb.x, mb.y, mb.z, mb.w};
.LBB0_213:
	s_andn2_saveexec_b64 s[8:9], s[8:9]
	s_cbranch_execz .LBB0_215
	v_lshl_add_u64 v[6:7], s[68:69], 0, v[58:59]
	v_lshl_add_u64 v[6:7], v[6:7], 0, v[70:71]
	global_load_dwordx4 v[6:9], v[6:7], off
.LBB0_215:
	s_or_b64 exec, exec, s[8:9]
	v_or_b32_e32 v69, 0xe40, v65
	v_readlane_b32 s8, v236, 18
	v_lshlrev_b32_e32 v70, 1, v69
	v_lshlrev_b32_e32 v62, 2, v65
	v_readlane_b32 s9, v236, 19
	v_lshl_add_u64 v[14:15], v[14:15], 0, v[70:71]
	s_nop 3
	global_load_dwordx4 v[18:21], v62, s[8:9] offset:16
	global_load_dwordx4 v[22:25], v62, s[8:9]
	global_load_dwordx4 v[26:29], v[14:15], off
	v_cmp_lt_i32_e32 vcc, 0, v64
	s_and_saveexec_b64 s[8:9], vcc
	s_xor_b64 s[8:9], exec, s[8:9]
	s_cbranch_execz .LBB0_219
	v_cmp_ne_u32_e32 vcc, 1, v64
	v_mov_b32_e32 v17, 0
	v_mov_b32_e32 v16, 0
	v_mov_b32_e32 v15, 0
	v_mov_b32_e32 v14, 0
	v_mov_b32_e32 v33, 0
	v_mov_b32_e32 v32, 0
	v_mov_b32_e32 v31, 0
	v_mov_b32_e32 v30, 0
	s_and_saveexec_b64 s[12:13], vcc
	s_cbranch_execz .LBB0_218
	s_add_u32 s16, s66, s29
	s_addc_u32 s17, s67, s27
	v_lshlrev_b32_e32 v70, 2, v69
	v_lshl_add_u64 v[14:15], s[16:17], 0, v[70:71]
	s_movk_i32 s16, 0xe000
	s_mov_b32 s17, -1
	v_lshl_add_u64 v[16:17], v[14:15], 0, s[16:17]
	v_add_co_u32_e32 v14, vcc, 0xffffe000, v14
	s_nop 1
	v_addc_co_u32_e32 v15, vcc, -1, v15, vcc
	global_load_dwordx4 v[30:33], v[14:15], off
	s_nop 0
	global_load_dwordx4 v[14:17], v[16:17], off offset:16

; DI void ld_cur_prev8(const Params& p, int row, int col, int mode, int sb, float* cur, float* prev) {
;     const u16* proj = (const u16*)(p.ws + W_PROJ);
;     unpack8(*(const uint4*)(proj + (size_t)row * NC + col), cur);
;     if (mode == 0) unpack8(*(const uint4*)(proj + (size_t)(row - 1) * NC + col), prev);
;     else if (mode == 1) { for (int i = 0; i < 8; ++i) prev[i] = 0.f; }
;     else { const float* s = p.st_shift + (size_t)sb * 1664 + (col - C_R); const float4 a = *(const float4*)s, b = *(const float4*)(s + 4);
;         prev[0] = a.x; prev[1] = a.y; prev[2] = a.z; prev[3] = a.w; prev[4] = b.x; prev[5] = b.y; prev[6] = b.z; prev[7] = b.w; }
; }
.LBB0_219:
	s_andn2_saveexec_b64 s[8:9], s[8:9]
	s_cbranch_execz .LBB0_221
	v_lshl_add_u64 v[14:15], s[68:69], 0, v[58:59]
	v_lshl_add_u64 v[14:15], v[14:15], 0, v[70:71]
	global_load_dwordx4 v[14:17], v[14:15], off
	s_waitcnt vmcnt(0)
	v_lshlrev_b32_e32 v10, 16, v6
	v_and_b32_e32 v11, 0xffff0000, v6
	v_lshlrev_b32_e32 v12, 16, v7
	v_and_b32_e32 v13, 0xffff0000, v7
	v_lshlrev_b32_e32 v6, 16, v8
	v_and_b32_e32 v7, 0xffff0000, v8
	v_lshlrev_b32_e32 v8, 16, v9
	v_and_b32_e32 v9, 0xffff0000, v9
	v_lshlrev_b32_e32 v30, 16, v14
	v_and_b32_e32 v31, 0xffff0000, v14
	v_lshlrev_b32_e32 v32, 16, v15
	v_and_b32_e32 v33, 0xffff0000, v15
	v_lshlrev_b32_e32 v14, 16, v16
	v_and_b32_e32 v15, 0xffff0000, v16
	v_lshlrev_b32_e32 v16, 16, v17
	v_and_b32_e32 v17, 0xffff0000, v17

; DI float rcpf_(float x) { return __builtin_amdgcn_rcpf(x); }
; DI void ld_cur_prev8(const Params& p, int row, int col, int mode, int sb, float* cur, float* prev) {
;     const u16* proj = (const u16*)(p.ws + W_PROJ);
;     unpack8(*(const uint4*)(proj + (size_t)row * NC + col), cur);
;     if (mode == 0) unpack8(*(const uint4*)(proj + (size_t)(row - 1) * NC + col), prev);
;     else if (mode == 1) { for (int i = 0; i < 8; ++i) prev[i] = 0.f; }
;     else { const float* s = p.st_shift + (size_t)sb * 1664 + (col - C_R); const float4 a = *(const float4*)s, b = *(const float4*)(s + 4);
;         prev[0] = a.x; prev[1] = a.y; prev[2] = a.z; prev[3] = a.w; prev[4] = b.x; prev[5] = b.y; prev[6] = b.z; prev[7] = b.w; }
; }
; DI void phase_rwkv_prep(const Params& p, char* lds) {
;     ...
;                     ld_cur_prev8(p, row0 + t, C_WD + cw, mode, b, cur, prv);
;                     { const float4 ma = *(const float4*)(p.mix + 1536 + cw), mb = *(const float4*)(p.mix + 1540 + cw); const float mx_[8] = {ma.x, ma.y, ma.z, ma.w, mb.x, mb.y, mb.z, mb.w};
; #pragma unroll
;                     for (int i = 0; i < 8; ++i) { const float x = cur[i] + (prv[i] - cur[i]) * mx_[i]; const float e2 = __expf(2.f * x); xw[i] = 1.f - 2.f * rcpf_(e2 + 1.f); } }
;                     ld_cur_prev8(p, row0 + t, C_AD + cw, mode, b, cur, prv);
;                     { const float4 ma = *(const float4*)(p.mix + 1600 + cw), mb = *(const float4*)(p.mix + 1604 + cw); const float mx_[8] = {ma.x, ma.y, ma.z, ma.w, mb.x, mb.y, mb.z, mb.w};
; #pragma unroll
;                     for (int i = 0; i < 8; ++i) xa[i] = cur[i] + (prv[i] - cur[i]) * mx_[i]; }
.LBB0_227:
	s_or_saveexec_b64 s[4:5], s[4:5]
	v_lshl_add_u64 v[58:59], s[68:69], 0, v[58:59]
	s_xor_b64 exec, exec, s[4:5]
	s_cbranch_execz .LBB0_229
	v_lshl_add_u64 v[6:7], v[58:59], 0, v[70:71]
	global_load_dwordx4 v[6:9], v[6:7], off
.LBB0_229:
	s_or_b64 exec, exec, s[4:5]
	v_or_b32_e32 v61, 0xe48, v65
	v_or_b32_e32 v16, 8, v65
	v_readlane_b32 s4, v236, 18
	v_lshlrev_b32_e32 v70, 1, v61
	v_lshlrev_b32_e32 v60, 2, v16
	v_readlane_b32 s5, v236, 19
	v_lshl_add_u64 v[14:15], v[14:15], 0, v[70:71]
	s_nop 3
	global_load_dwordx4 v[18:21], v60, s[4:5] offset:16
	global_load_dwordx4 v[22:25], v60, s[4:5]
	global_load_dwordx4 v[26:29], v[14:15], off
	v_cmp_lt_i32_e32 vcc, 0, v64
	s_and_saveexec_b64 s[4:5], vcc
	s_xor_b64 s[4:5], exec, s[4:5]
	s_cbranch_execz .LBB0_233
	v_cmp_ne_u32_e32 vcc, 1, v64
	v_mov_b32_e32 v17, 0
	v_mov_b32_e32 v16, 0
	v_mov_b32_e32 v15, 0
	v_mov_b32_e32 v14, 0
	v_mov_b32_e32 v33, 0
	v_mov_b32_e32 v32, 0
	v_mov_b32_e32 v31, 0
	v_mov_b32_e32 v30, 0
	s_and_saveexec_b64 s[8:9], vcc
	s_cbranch_execz .LBB0_232
	s_add_u32 s12, s66, s29
	s_addc_u32 s13, s67, s27
	v_lshlrev_b32_e32 v70, 2, v61
	v_lshl_add_u64 v[14:15], s[12:13], 0, v[70:71]
	s_movk_i32 s12, 0xe000
	s_mov_b32 s13, -1
	v_lshl_add_u64 v[16:17], v[14:15], 0, s[12:13]
	v_add_co_u32_e32 v14, vcc, 0xffffe000, v14
	s_nop 1
	v_addc_co_u32_e32 v15, vcc, -1, v15, vcc
	global_load_dwordx4 v[30:33], v[14:15], off
	s_nop 0
	global_load_dwordx4 v[14:17], v[16:17], off offset:16

; DI void ld_cur_prev8(const Params& p, int row, int col, int mode, int sb, float* cur, float* prev) {
;     const u16* proj = (const u16*)(p.ws + W_PROJ);
;     unpack8(*(const uint4*)(proj + (size_t)row * NC + col), cur);
;     if (mode == 0) unpack8(*(const uint4*)(proj + (size_t)(row - 1) * NC + col), prev);
;     else if (mode == 1) { for (int i = 0; i < 8; ++i) prev[i] = 0.f; }
;     else { const float* s = p.st_shift + (size_t)sb * 1664 + (col - C_R); const float4 a = *(const float4*)s, b = *(const float4*)(s + 4);
;         prev[0] = a.x; prev[1] = a.y; prev[2] = a.z; prev[3] = a.w; prev[4] = b.x; prev[5] = b.y; prev[6] = b.z; prev[7] = b.w; }
; }
; DI void phase_rwkv_prep(const Params& p, char* lds) {
;     ...
;                     ld_cur_prev8(p, row0 + t, C_AD + cw, mode, b, cur, prv);
;                     { const float4 ma = *(const float4*)(p.mix + 1600 + cw), mb = *(const float4*)(p.mix + 1604 + cw); const float mx_[8] = {ma.x, ma.y, ma.z, ma.w, mb.x, mb.y, mb.z, mb.w};
; #pragma unroll
;                     for (int i = 0; i < 8; ++i) xa[i] = cur[i] + (prv[i] - cur[i]) * mx_[i]; }
.LBB0_233:
	s_andn2_saveexec_b64 s[4:5], s[4:5]
	s_cbranch_execz .LBB0_235
	v_lshl_add_u64 v[14:15], v[58:59], 0, v[70:71]
	global_load_dwordx4 v[14:17], v[14:15], off
	s_waitcnt vmcnt(0)
	v_lshlrev_b32_e32 v10, 16, v6
	v_and_b32_e32 v11, 0xffff0000, v6
	v_lshlrev_b32_e32 v12, 16, v7
	v_and_b32_e32 v13, 0xffff0000, v7
	v_lshlrev_b32_e32 v6, 16, v8
	v_and_b32_e32 v7, 0xffff0000, v8
	v_lshlrev_b32_e32 v8, 16, v9
	v_and_b32_e32 v9, 0xffff0000, v9
	v_lshlrev_b32_e32 v30, 16, v14
	v_and_b32_e32 v31, 0xffff0000, v14
	v_lshlrev_b32_e32 v32, 16, v15
	v_and_b32_e32 v33, 0xffff0000, v15
	v_lshlrev_b32_e32 v14, 16, v16
	v_and_b32_e32 v15, 0xffff0000, v16
	v_lshlrev_b32_e32 v16, 16, v17
	v_and_b32_e32 v17, 0xffff0000, v17

; DI unsigned pack2(float lo, float hi) { f32x2_t v = {lo, hi}; bf16x2_t b = __builtin_convertvector(v, bf16x2_t); return __builtin_bit_cast(unsigned, b); }
; DI void phase_rwkv_prep(const Params& p, char* lds) {
;     ...
;                     ow.x = pack2(xw[0], xw[1]); ow.y = pack2(xw[2], xw[3]); ow.z = pack2(xw[4], xw[5]); ow.w = pack2(xw[6], xw[7]);
;                     oa.x = pack2(xa[0], xa[1]); oa.y = pack2(xa[2], xa[3]); oa.z = pack2(xa[4], xa[5]); oa.w = pack2(xa[6], xa[7]);
;                 }
;                 *(uint4*)(R0 + swz(t, 2 * q + half)) = ow; *(uint4*)(R1 + swz(t, 2 * q + half)) = oa;
;             }
;         }
;         __syncthreads();
;         {
;             f32x16 adw, ada;
; #pragma unroll
;             for (int e = 0; e < 16; ++e) { adw[e] = 0.f; ada[e] = 0.f; }
;             const u16* wup = (const u16*)(p.ws + W_WUPT) + (size_t)(h * 64 + 32 * qn + r) * 64; const u16* aup = (const u16*)(p.ws + W_AUPT) + (size_t)(h * 64 + 32 * qn + r) * 64;
; #pragma unroll
;             for (int ks = 0; ks < 4; ++ks) {
;                 const bf16x8 xa = *(const bf16x8*)(R0 + swz(32 * qm + r, 2 * ks + h5)); const bf16x8 xb = *(const bf16x8*)(R1 + swz(32 * qm + r, 2 * ks + h5));
;                 const bf16x8 ya = *(const bf16x8*)(wup + 16 * ks + 8 * h5); const bf16x8 yb = *(const bf16x8*)(aup + 16 * ks + 8 * h5);
;                 adw = __builtin_amdgcn_mfma_f32_32x32x16_bf16(xa, ya, adw, 0, 0, 0); ada = __builtin_amdgcn_mfma_f32_32x32x16_bf16(xb, yb, ada, 0, 0, 0);
;             }
;             float* DW = (float*)R4; float* DA = (float*)R6; const int n = 32 * qn + r;
; #pragma unroll
;             for (int e = 0; e < 16; ++e) { const int m = 32 * qm + (e & 3) + 8 * (e >> 2) + 4 * h5; DW[m * 64 + n] = adw[e]; DA[m * 64 + n] = ada[e]; }
;         }
;         __syncthreads();
;         {
;             const int tg = wave, j = lane, hj = h * 64 + j;
;             float* DW = (float*)R4; const float* DA = (const float*)R6;
;             { const float w0j = p.w0[hj];
;                 float run = 0.f;
; #pragma unroll 4
;                 for (int i = 0; i < 16; ++i) { const int t = 16 * tg + i; const float x = w0j + DW[t * 64 + j];
;                     const float z = -x; const float sp = fmaxf(z, 0.f) + __logf(1.f + __expf(-fabsf(z))); float l = -__expf(-sp - 0.5f); if (t >= ntok) l = 0.f; DW[t * 64 + j] = l; run += l; }
.LBB0_236:
	v_writelane_b32 v236, s15, 11
	s_or_b64 exec, exec, s[6:7]
	v_bfe_u32 v10, v63, 1, 3
	s_and_b32 s4, s14, 1
	v_bitop3_b32 v10, v68, v10, 1 bitop3:0x36
	v_lshl_or_b32 v10, v10, 4, v72
	s_lshl_b32 s33, s4, 5
	v_and_b32_e32 v11, 31, v66
	v_add_u32_e32 v10, 0, v10
	v_writelane_b32 v236, s4, 35
	s_or_b32 s4, s33, s31
	ds_write_b128 v10, v[6:9]
	ds_write_b128 v10, v[2:5] offset:8192
	v_or_b32_e32 v2, s4, v11
	v_readlane_b32 s4, v236, 22
	v_lshlrev_b32_e32 v70, 7, v2
	v_readlane_b32 s5, v236, 23
	v_lshrrev_b32_e32 v69, 5, v62
	v_lshl_add_u64 v[2:3], s[4:5], 0, v[70:71]
	v_readlane_b32 s4, v236, 24
	v_readlane_b32 s5, v236, 25
	s_nop 0
	v_lshl_add_u64 v[6:7], s[4:5], 0, v[70:71]
	v_lshlrev_b32_e32 v70, 4, v69
	v_lshl_add_u64 v[8:9], v[2:3], 0, v[70:71]
	global_load_dwordx4 v[2:5], v[8:9], off
	v_lshl_add_u64 v[6:7], v[6:7], 0, v[70:71]
	global_load_dwordx4 v[18:21], v[6:7], off
	global_load_dwordx4 v[76:79], v[8:9], off offset:32
	global_load_dwordx4 v[80:83], v[6:7], off offset:32
	global_load_dwordx4 v[84:87], v[8:9], off offset:64
	global_load_dwordx4 v[88:91], v[6:7], off offset:64
	global_load_dwordx4 v[92:95], v[8:9], off offset:96
	global_load_dwordx4 v[96:99], v[6:7], off offset:96
	s_waitcnt lgkmcnt(0)
	s_barrier
	s_ashr_i32 s51, s3, 7
	v_lshrrev_b32_e32 v8, 1, v66
	s_lshl_b32 s5, s51, 12
	v_bitop3_b32 v6, v69, v8, 7 bitop3:0x78
	v_lshl_or_b32 v64, v11, 7, s5
	v_lshlrev_b32_e32 v61, 4, v6
	v_bfe_u32 v68, v66, 1, 3
	v_or_b32_e32 v6, v61, v64
	v_bitop3_b32 v7, v69, v68, 2 bitop3:0x36
	v_add_u32_e32 v13, 0, v6
	v_lshlrev_b32_e32 v60, 4, v7
	ds_read_b128 v[6:9], v13
	ds_read_b128 v[22:25], v13 offset:8192
	v_or_b32_e32 v26, v60, v64
	v_add_u32_e32 v65, 0, v26
	v_bitop3_b32 v10, v69, v68, 4 bitop3:0x36
	v_bitop3_b32 v12, v69, v68, 6 bitop3:0x36
	ds_read_b128 v[100:103], v65
	ds_read_b128 v[104:107], v65 offset:8192
	v_lshlrev_b32_e32 v59, 4, v10
	v_lshlrev_b32_e32 v58, 4, v12
	v_or_b32_e32 v74, s33, v11
	v_or_b32_e32 v70, v59, v64
	v_add_u32_e32 v65, 0, v70
	v_or_b32_e32 v64, v58, v64
	v_add_u32_e32 v64, 0, v64
	s_lshl_b32 s92, s51, 5
	v_writelane_b32 v236, s5, 36
	s_or_b32 s17, s92, 1
	s_or_b32 s5, s92, 2
	v_writelane_b32 v236, s17, 37
	s_or_b32 s6, s92, 3
	v_writelane_b32 v236, s5, 38
	s_or_b32 s7, s92, 8
	v_writelane_b32 v236, s6, 17
	s_or_b32 s8, s92, 9
	v_writelane_b32 v236, s7, 14
	s_or_b32 s9, s92, 10
	v_writelane_b32 v236, s8, 39
	s_or_b32 s12, s92, 11
	v_writelane_b32 v236, s9, 15
	s_or_b32 s13, s92, 16
	v_writelane_b32 v236, s12, 13
	s_or_b32 s15, s92, 17
	v_writelane_b32 v236, s13, 12
	v_lshlrev_b32_e32 v63, 8, v69
	s_lshl_b32 s4, s51, 11
	s_or_b32 s16, s92, 18
	v_writelane_b32 v236, s15, 40
	v_or3_b32 v72, v63, s4, v74
	s_lshl_b32 s4, s17, 6
	s_lshl_b32 s5, s5, 6
	s_lshl_b32 s6, s6, 6
	s_lshl_b32 s7, s7, 6
	s_lshl_b32 s8, s8, 6
	s_lshl_b32 s9, s9, 6
	s_lshl_b32 s12, s12, 6
	s_waitcnt vmcnt(6) lgkmcnt(2)
	v_mfma_f32_32x32x16_bf16 v[18:33], v[22:25], v[18:21], 0
	s_lshl_b32 s13, s13, 6
	s_lshl_b32 s15, s15, 6
	v_writelane_b32 v236, s16, 16
	s_lshl_b32 s16, s16, 6
	v_lshl_add_u32 v70, v72, 2, 0
	v_or3_b32 v72, s5, v63, v74
	v_or3_b32 v75, s6, v63, v74
	v_mfma_f32_32x32x16_bf16 v[2:17], v[6:9], v[2:5], 0
	s_waitcnt vmcnt(5) lgkmcnt(1)
	v_mfma_f32_32x32x16_bf16 v[2:17], v[100:103], v[76:79], v[2:17]
	ds_read_b128 v[76:79], v65
	s_waitcnt vmcnt(4) lgkmcnt(1)
	v_mfma_f32_32x32x16_bf16 v[18:33], v[104:107], v[80:83], v[18:33]
	ds_read_b128 v[80:83], v65 offset:8192
	v_or3_b32 v65, s4, v63, v74
	s_or_b32 s4, s92, 19
	v_writelane_b32 v236, s4, 41
	s_lshl_b32 s4, s4, 6
	s_waitcnt vmcnt(3) lgkmcnt(1)
	v_mfma_f32_32x32x16_bf16 v[2:17], v[76:79], v[84:87], v[2:17]
	ds_read_b128 v[76:79], v64
	v_or3_b32 v84, s7, v63, v74
	v_or3_b32 v85, s8, v63, v74
	v_or3_b32 v86, s9, v63, v74
	v_or3_b32 v87, s12, v63, v74
	s_mov_b32 s12, 0
	s_waitcnt vmcnt(2) lgkmcnt(1)
	v_mfma_f32_32x32x16_bf16 v[18:33], v[80:83], v[88:91], v[18:33]
	ds_read_b128 v[80:83], v64 offset:8192
	v_or3_b32 v88, s13, v63, v74
	v_or3_b32 v89, s15, v63, v74
	v_or3_b32 v90, s16, v63, v74
	v_lshl_add_u32 v64, v65, 2, 0
	v_lshl_add_u32 v65, v72, 2, 0
	v_lshl_add_u32 v72, v75, 2, 0
	s_waitcnt vmcnt(1) lgkmcnt(1)
	v_mfma_f32_32x32x16_bf16 v[2:17], v[76:79], v[92:95], v[2:17]
	v_lshl_add_u32 v75, v84, 2, 0
	v_lshl_add_u32 v76, v85, 2, 0
	v_lshl_add_u32 v77, v86, 2, 0
	v_lshl_add_u32 v78, v87, 2, 0
	v_lshl_add_u32 v79, v88, 2, 0
	v_lshl_add_u32 v84, v89, 2, 0
	s_mov_b32 s13, s10
	s_waitcnt vmcnt(0) lgkmcnt(0)
	v_mfma_f32_32x32x16_bf16 v[18:33], v[80:83], v[96:99], v[18:33]
	s_nop 11
	ds_write2st64_b32 v70, v2, v18 offset0:128 offset1:192
	ds_write2st64_b32 v64, v3, v19 offset0:128 offset1:192
	ds_write2st64_b32 v65, v4, v20 offset0:128 offset1:192
	ds_write2st64_b32 v72, v5, v21 offset0:128 offset1:192
	ds_write2st64_b32 v75, v6, v22 offset0:128 offset1:192
	ds_write2st64_b32 v76, v7, v23 offset0:128 offset1:192
	ds_write2st64_b32 v77, v8, v24 offset0:128 offset1:192
	ds_write2st64_b32 v78, v9, v25 offset0:128 offset1:192
	ds_write2st64_b32 v79, v10, v26 offset0:128 offset1:192
	ds_write2st64_b32 v84, v11, v27 offset0:128 offset1:192
	v_lshl_add_u32 v2, v90, 2, 0
	ds_write2st64_b32 v2, v12, v28 offset0:128 offset1:192
	v_or3_b32 v2, s4, v63, v74
	s_or_b32 s4, s92, 24
	v_lshl_add_u32 v2, v2, 2, 0
	v_writelane_b32 v236, s4, 42
	s_lshl_b32 s4, s4, 6
	ds_write2st64_b32 v2, v13, v29 offset0:128 offset1:192
	v_or3_b32 v2, s4, v63, v74
	s_or_b32 s4, s92, 25
	v_lshl_add_u32 v2, v2, 2, 0
	v_writelane_b32 v236, s4, 43
	s_lshl_b32 s4, s4, 6
	ds_write2st64_b32 v2, v14, v30 offset0:128 offset1:192
	v_or3_b32 v2, s4, v63, v74
	s_or_b32 s4, s92, 26
	v_lshl_add_u32 v2, v2, 2, 0
	v_writelane_b32 v236, s4, 44
	s_lshl_b32 s4, s4, 6
	ds_write2st64_b32 v2, v15, v31 offset0:128 offset1:192
	v_or3_b32 v2, s4, v63, v74
	s_or_b32 s4, s92, 27
	v_lshl_add_u32 v2, v2, 2, 0
	v_writelane_b32 v236, s4, 45
	s_lshl_b32 s4, s4, 6
	ds_write2st64_b32 v2, v16, v32 offset0:128 offset1:192
	v_or3_b32 v2, s4, v63, v74
	v_lshl_add_u32 v2, v2, 2, 0
	ds_write2st64_b32 v2, v17, v33 offset0:128 offset1:192
	v_or_b32_e32 v2, s31, v62
	v_lshlrev_b32_e32 v3, 2, v2
	global_load_dword v3, v3, s[80:81]
	s_waitcnt lgkmcnt(0)
	s_barrier
	s_lshl_b32 s4, s14, 12
	s_add_i32 s4, s4, 0
	s_add_i32 s4, s4, 0x8000
	v_lshlrev_b32_e32 v72, 3, v69
	v_lshl_add_u32 v4, v62, 2, s4
	v_mov_b32_e32 v5, 0

; DI float bf2f(u16 h) { return __uint_as_float((unsigned)h << 16); }
; DI float ld_prev1(const Params& p, int row, int col, int mode, int sb) {
;     const u16* proj = (const u16*)(p.ws + W_PROJ);
;     if (mode == 0) return bf2f(proj[(size_t)(row - 1) * NC + col]);
;     if (mode == 1) return 0.f;
;     return p.st_shift[(size_t)sb * 1664 + (col - C_R)];
; }
; DI void phase_rwkv_prep(const Params& p, char* lds) {
;     ...
;             { const int t0 = 16 * tg; if (t0 < ntok) { const int mode = t0 > 0 ? 0 : mode0; pr = ld_prev1(p, row0 + t0, C_R + hj, mode, b); pk = ld_prev1(p, row0 + t0, C_RK + hj, mode, b); pv = ld_prev1(p, row0 + t0, C_RV + hj, mode, b); } }
.LBB0_252:
	s_add_i32 s2, s11, -1
	s_mul_hi_i32 s3, s2, 0x2100
	s_mulk_i32 s2, 0x2100
	s_add_u32 s2, s68, s2
	s_addc_u32 s3, s69, s3
	v_lshlrev_b32_e32 v8, 1, v9
	global_load_ushort v8, v8, s[2:3]
	v_or_b32_e32 v30, 0xa00, v2
	s_cmp_lt_i32 s7, 1
	s_mov_b64 s[2:3], -1
	s_cbranch_scc0 .LBB0_246

; DI float bf2f(u16 h) { return __uint_as_float((unsigned)h << 16); }
; DI float ld_prev1(const Params& p, int row, int col, int mode, int sb) {
;     const u16* proj = (const u16*)(p.ws + W_PROJ);
;     if (mode == 0) return bf2f(proj[(size_t)(row - 1) * NC + col]);
;     if (mode == 1) return 0.f;
;     return p.st_shift[(size_t)sb * 1664 + (col - C_R)];
; }
; DI void phase_rwkv_prep(const Params& p, char* lds) {
;     ...
;             { const int t0 = 16 * tg; if (t0 < ntok) { const int mode = t0 > 0 ? 0 : mode0; pr = ld_prev1(p, row0 + t0, C_R + hj, mode, b); pk = ld_prev1(p, row0 + t0, C_RK + hj, mode, b); pv = ld_prev1(p, row0 + t0, C_RV + hj, mode, b); } }
.LBB0_254:
	s_add_i32 s2, s11, -1
	s_mul_hi_i32 s3, s2, 0x2100
	s_mulk_i32 s2, 0x2100
	s_add_u32 s2, s68, s2
	s_addc_u32 s3, s69, s3
	v_lshlrev_b32_e32 v9, 1, v30
	global_load_ushort v9, v9, s[2:3]

; DI float bf2f(u16 h) { return __uint_as_float((unsigned)h << 16); }
; DI float ld_prev1(const Params& p, int row, int col, int mode, int sb) {
;     const u16* proj = (const u16*)(p.ws + W_PROJ);
;     if (mode == 0) return bf2f(proj[(size_t)(row - 1) * NC + col]);
;     if (mode == 1) return 0.f;
;     return p.st_shift[(size_t)sb * 1664 + (col - C_R)];
; }
; DI void phase_rwkv_prep(const Params& p, char* lds) {
;     ...
;             { const int t0 = 16 * tg; if (t0 < ntok) { const int mode = t0 > 0 ? 0 : mode0; pr = ld_prev1(p, row0 + t0, C_R + hj, mode, b); pk = ld_prev1(p, row0 + t0, C_RK + hj, mode, b); pv = ld_prev1(p, row0 + t0, C_RV + hj, mode, b); } }
.LBB0_264:
	s_add_i32 s2, s11, -1
	s_mul_hi_i32 s3, s2, 0x2100
	s_mulk_i32 s2, 0x2100
	s_add_u32 s2, s68, s2
	s_addc_u32 s3, s69, s3
	v_lshlrev_b32_e32 v2, 1, v2
	global_load_ushort v2, v2, s[2:3]
	s_waitcnt vmcnt(0)
	v_lshlrev_b32_e32 v8, 16, v8
	v_lshlrev_b32_e32 v9, 16, v9
	v_lshlrev_b32_e32 v47, 16, v2
	s_and_b64 vcc, exec, s[0:1]
	v_mov_b32_e32 v30, 0
	s_cbranch_vccz .LBB0_260
	s_branch .LBB0_250
